# v109 plus wait-state padding: readlane to VALU SGPR read in the wave_sum tails, VALU to DPP in the two norm loops
# speedup vs baseline: 1.0291x; 1.0082x over previous
.LBB0_253:
	v_ashrrev_i32_e32 v45, 31, v44
	v_lshlrev_b64 v[18:19], 12, v[44:45]
	v_lshl_add_u64 v[18:19], v[38:39], 0, v[18:19]
	v_lshlrev_b64 v[92:93], 11, v[44:45]
	global_load_dwordx4 v[34:37], v[18:19], off nt
	global_load_dwordx4 v[56:59], v[18:19], off offset:1024 nt
	global_load_dwordx4 v[76:79], v[18:19], off offset:2048 nt
	global_load_dwordx4 v[80:83], v[18:19], off offset:3072 nt
	v_lshl_add_u64 v[18:19], v[40:41], 0, v[92:93]
	global_load_dwordx2 v[70:71], v[18:19], off
	global_load_dwordx2 v[84:85], v[18:19], off offset:512
	global_load_dwordx2 v[86:87], v[18:19], off offset:1024
	global_load_dwordx2 v[94:95], v[18:19], off offset:1536
	v_ashrrev_i32_e32 v45, 10, v1
	v_mul_hi_i32_i24_e32 v69, 0x6000, v45
	v_mul_i32_i24_e32 v68, 0x6000, v45
	v_lshl_add_u64 v[68:69], s[6:7], 0, v[68:69]
	s_mov_b64 s[2:3], 0x4000
	v_lshl_add_u64 v[74:75], v[68:69], 0, s[2:3]
	s_mov_b64 s[2:3], 0x3000
	v_lshl_add_u64 v[72:73], v[68:69], 0, s[2:3]
	v_add_u32_e32 v54, 1, v44
	v_ashrrev_i32_e32 v55, 31, v54
	v_lshlrev_b64 v[18:19], 12, v[54:55]
	v_lshlrev_b64 v[54:55], 11, v[54:55]
	v_mov_b32_e32 v47, v0
	v_lshl_add_u64 v[18:19], v[38:39], 0, v[18:19]
	v_lshl_add_u64 v[60:61], v[40:41], 0, v[54:55]
	v_lshl_add_u64 v[68:69], v[74:75], 0, v[46:47]
	global_load_dwordx4 v[176:179], v[68:69], off
	global_load_dwordx4 v[180:183], v[68:69], off offset:1024
	global_load_dwordx4 v[184:187], v[68:69], off offset:2048
	global_load_dwordx4 v[188:191], v[68:69], off offset:3072
	v_lshl_add_u64 v[208:209], v[72:73], 0, v[46:47]
	global_load_dwordx4 v[192:195], v[208:209], off
	global_load_dwordx4 v[196:199], v[208:209], off offset:1024
	global_load_dwordx4 v[200:203], v[208:209], off offset:2048
	global_load_dwordx4 v[204:207], v[208:209], off offset:3072
	global_load_dwordx4 v[30:33], v[18:19], off nt
	global_load_dwordx4 v[26:29], v[18:19], off offset:1024 nt
	global_load_dwordx4 v[22:25], v[18:19], off offset:2048 nt
	s_nop 0
	global_load_dwordx4 v[18:21], v[18:19], off offset:3072 nt
	s_nop 0
	global_load_dwordx2 v[66:67], v[60:61], off
	global_load_dwordx2 v[64:65], v[60:61], off offset:512
	global_load_dwordx2 v[62:63], v[60:61], off offset:1024
	s_nop 0
	global_load_dwordx2 v[60:61], v[60:61], off offset:1536
	v_mov_b32_e32 v49, v0
	v_mov_b32_e32 v51, v0
	v_mov_b32_e32 v53, v0
	v_lshl_add_u64 v[54:55], v[42:43], 0, v[54:55]
	v_add_u32_e32 v1, s33, v1
	v_add_u32_e32 v44, s95, v44
	s_waitcnt vmcnt(0)
	v_lshlrev_b32_e32 v88, 16, v70
	v_and_b32_e32 v89, 0xffff0000, v70
	v_pk_add_f32 v[96:97], v[34:35], v[88:89]
	v_lshlrev_b32_e32 v34, 16, v71
	v_and_b32_e32 v35, 0xffff0000, v71
	v_pk_add_f32 v[98:99], v[36:37], v[34:35]
	v_mov_b32_e32 v36, v97
	v_mov_b32_e32 v37, v99
	v_mov_b32_e32 v34, v96
	v_mov_b32_e32 v35, v98
	v_pk_mul_f32 v[36:37], v[36:37], v[36:37]
	v_lshlrev_b32_e32 v70, 16, v94
	v_pk_fma_f32 v[34:35], v[34:35], v[34:35], v[36:37]
	v_lshlrev_b32_e32 v36, 16, v84
	v_and_b32_e32 v37, 0xffff0000, v84
	v_pk_add_f32 v[88:89], v[56:57], v[36:37]
	v_lshlrev_b32_e32 v36, 16, v85
	v_and_b32_e32 v37, 0xffff0000, v85
	v_pk_add_f32 v[90:91], v[58:59], v[36:37]
	v_mov_b32_e32 v56, v89
	v_mov_b32_e32 v57, v91
	v_mov_b32_e32 v36, v88
	v_mov_b32_e32 v37, v90
	v_pk_mul_f32 v[56:57], v[56:57], v[56:57]
	v_and_b32_e32 v71, 0xffff0000, v94
	v_pk_fma_f32 v[36:37], v[36:37], v[36:37], v[56:57]
	v_lshlrev_b32_e32 v56, 16, v86
	v_and_b32_e32 v57, 0xffff0000, v86
	v_pk_add_f32 v[84:85], v[76:77], v[56:57]
	v_lshlrev_b32_e32 v56, 16, v87
	v_and_b32_e32 v57, 0xffff0000, v87
	v_pk_add_f32 v[86:87], v[78:79], v[56:57]
	v_pk_add_f32 v[76:77], v[80:81], v[70:71]
	v_lshlrev_b32_e32 v70, 16, v95
	v_and_b32_e32 v71, 0xffff0000, v95
	v_mul_f32_e32 v56, v85, v85
	v_mul_f32_e32 v58, v87, v87
	v_pk_add_f32 v[78:79], v[82:83], v[70:71]
	v_pk_add_f32 v[34:35], v[34:35], v[34:35] op_sel:[0,1] op_sel_hi:[1,0]
	v_pk_add_f32 v[36:37], v[36:37], v[36:37] op_sel:[0,1] op_sel_hi:[1,0]
	v_pk_fma_f32 v[56:57], v[84:85], v[84:85], v[56:57] op_sel_hi:[1,1,0]
	v_pk_fma_f32 v[58:59], v[86:87], v[86:87], v[58:59] op_sel_hi:[1,1,0]
	v_pk_mul_f32 v[70:71], v[76:77], v[76:77]
	v_pk_mul_f32 v[80:81], v[78:79], v[78:79]
	v_mov_b32_e32 v35, v70
	v_mov_b32_e32 v37, v71
	v_mov_b32_e32 v57, v80
	v_mov_b32_e32 v59, v81
	v_pk_add_f32 v[34:35], v[34:35], v[36:37]
	v_pk_add_f32 v[36:37], v[56:57], v[58:59]
	v_lshl_add_u64 v[70:71], v[72:73], 0, v[46:47]
	v_pk_add_f32 v[34:35], v[34:35], v[36:37]
	v_mov_b64_e32 v[56:57], v[192:193]
	v_mov_b64_e32 v[58:59], v[194:195]
	v_add_f32_e32 v34, v34, v35
	s_nop 1
	v_add_f32_dpp v34, v34, v34 quad_perm:[1,0,3,2] row_mask:0xf bank_mask:0xf bound_ctrl:1
	s_nop 1
	v_add_f32_dpp v34, v34, v34 quad_perm:[2,3,0,1] row_mask:0xf bank_mask:0xf bound_ctrl:1
	s_nop 1
	v_add_f32_dpp v34, v34, v34 row_half_mirror row_mask:0xf bank_mask:0xf bound_ctrl:1
	s_nop 1
	v_add_f32_dpp v34, v34, v34 row_mirror row_mask:0xf bank_mask:0xf bound_ctrl:1
	s_nop 0
	v_readlane_b32 s8, v34, 16
	v_readlane_b32 s9, v34, 48
	v_readlane_b32 s2, v34, 0
	v_readlane_b32 s3, v34, 32
	v_mov_b32_e32 v34, s8
	v_mov_b32_e32 v35, s9
	v_pk_add_f32 v[34:35], s[2:3], v[34:35]
	s_nop 0
	v_add_f32_e32 v34, v34, v35
	v_fmamk_f32 v34, v34, 0x3a800000, v162
	v_cmp_gt_f32_e32 vcc, s82, v34
	v_mul_f32_e32 v35, 0x4b800000, v34
	s_nop 0
	v_cndmask_b32_e32 v34, v34, v35, vcc
	v_rsq_f32_e32 v34, v34
	s_nop 0
	v_mul_f32_e32 v35, 0x45800000, v34
	v_cndmask_b32_e32 v80, v34, v35, vcc
	v_mov_b64_e32 v[34:35], v[176:177]
	v_mov_b64_e32 v[36:37], v[178:179]
	v_pk_mul_f32 v[82:83], v[98:99], v[80:81] op_sel_hi:[1,0]
	v_pk_mul_f32 v[94:95], v[96:97], v[80:81] op_sel_hi:[1,0]
	v_pk_mul_f32 v[82:83], v[4:5], v[82:83]
	v_pk_mul_f32 v[94:95], v[2:3], v[94:95]
	v_pk_mul_f32 v[88:89], v[88:89], v[80:81] op_sel_hi:[1,0]
	v_pk_mul_f32 v[90:91], v[90:91], v[80:81] op_sel_hi:[1,0]
	v_pk_mul_f32 v[88:89], v[6:7], v[88:89]
	v_pk_mul_f32 v[90:91], v[8:9], v[90:91]
	v_pk_mul_f32 v[84:85], v[84:85], v[80:81] op_sel_hi:[1,0]
	v_pk_mul_f32 v[86:87], v[86:87], v[80:81] op_sel_hi:[1,0]
	v_pk_mul_f32 v[84:85], v[10:11], v[84:85]
	v_pk_mul_f32 v[86:87], v[12:13], v[86:87]
	v_pk_mul_f32 v[76:77], v[76:77], v[80:81] op_sel_hi:[1,0]
	v_pk_mul_f32 v[78:79], v[78:79], v[80:81] op_sel_hi:[1,0]
	v_pk_mul_f32 v[76:77], v[14:15], v[76:77]
	v_pk_mul_f32 v[78:79], v[16:17], v[78:79]
	v_pk_add_f32 v[36:37], v[36:37], 1.0 op_sel_hi:[1,0]
	v_pk_add_f32 v[34:35], v[34:35], 1.0 op_sel_hi:[1,0]
	v_pk_fma_f32 v[36:37], v[36:37], v[82:83], v[58:59]
	v_pk_fma_f32 v[34:35], v[34:35], v[94:95], v[56:57]
	v_lshl_add_u64 v[82:83], v[42:43], 0, v[92:93]
	v_cvt_pk_bf16_f32 v34, v34, v35
	v_cvt_pk_bf16_f32 v35, v36, v37
	global_store_dwordx2 v[82:83], v[34:35], off
	v_lshl_add_u64 v[56:57], v[74:75], 0, v[48:49]
	v_mov_b64_e32 v[34:35], v[180:181]
	v_mov_b64_e32 v[36:37], v[182:183]
	v_lshl_add_u64 v[58:59], v[72:73], 0, v[48:49]
	v_mov_b64_e32 v[92:93], v[196:197]
	v_mov_b64_e32 v[94:95], v[198:199]
	v_pk_add_f32 v[34:35], v[34:35], 1.0 op_sel_hi:[1,0]
	v_pk_add_f32 v[36:37], v[36:37], 1.0 op_sel_hi:[1,0]
	v_pk_fma_f32 v[34:35], v[34:35], v[88:89], v[92:93]
	v_pk_fma_f32 v[36:37], v[36:37], v[90:91], v[94:95]
	v_cvt_pk_bf16_f32 v34, v34, v35
	s_nop 0
	v_cvt_pk_bf16_f32 v35, v36, v37
	global_store_dwordx2 v[82:83], v[34:35], off offset:512
	v_lshl_add_u64 v[34:35], v[74:75], 0, v[50:51]
	v_mov_b64_e32 v[88:89], v[184:185]
	v_mov_b64_e32 v[90:91], v[186:187]
	v_lshl_add_u64 v[36:37], v[72:73], 0, v[50:51]
	v_mov_b64_e32 v[92:93], v[200:201]
	v_mov_b64_e32 v[94:95], v[202:203]
	v_lshl_add_u64 v[74:75], v[74:75], 0, v[52:53]
	v_lshl_add_u64 v[72:73], v[72:73], 0, v[52:53]
	v_pk_add_f32 v[88:89], v[88:89], 1.0 op_sel_hi:[1,0]
	v_pk_add_f32 v[90:91], v[90:91], 1.0 op_sel_hi:[1,0]
	v_pk_fma_f32 v[84:85], v[88:89], v[84:85], v[92:93]
	v_pk_fma_f32 v[86:87], v[90:91], v[86:87], v[94:95]
	v_cvt_pk_bf16_f32 v84, v84, v85
	s_nop 0
	v_cvt_pk_bf16_f32 v85, v86, v87
	global_store_dwordx2 v[82:83], v[84:85], off offset:1024
	v_mov_b64_e32 v[84:85], v[188:189]
	v_mov_b64_e32 v[86:87], v[190:191]
	s_nop 0
	v_mov_b64_e32 v[88:89], v[204:205]
	v_mov_b64_e32 v[90:91], v[206:207]
	v_pk_add_f32 v[84:85], v[84:85], 1.0 op_sel_hi:[1,0]
	v_pk_add_f32 v[80:81], v[86:87], 1.0 op_sel_hi:[1,0]
	v_pk_fma_f32 v[76:77], v[76:77], v[84:85], v[88:89]
	v_pk_fma_f32 v[78:79], v[78:79], v[80:81], v[90:91]
	v_cvt_pk_bf16_f32 v76, v76, v77
	s_nop 0
	v_cvt_pk_bf16_f32 v77, v78, v79
	global_store_dwordx2 v[82:83], v[76:77], off offset:1536
	v_lshlrev_b32_e32 v76, 16, v66
	v_and_b32_e32 v77, 0xffff0000, v66
	v_pk_add_f32 v[76:77], v[30:31], v[76:77]
	v_lshlrev_b32_e32 v30, 16, v67
	v_and_b32_e32 v31, 0xffff0000, v67
	v_pk_add_f32 v[32:33], v[32:33], v[30:31]
	v_mov_b32_e32 v66, v77
	v_mov_b32_e32 v67, v33
	v_mov_b32_e32 v30, v76
	v_mov_b32_e32 v31, v32
	v_pk_mul_f32 v[66:67], v[66:67], v[66:67]
	v_lshlrev_b32_e32 v78, 16, v60
	v_pk_fma_f32 v[30:31], v[30:31], v[30:31], v[66:67]
	v_lshlrev_b32_e32 v66, 16, v64
	v_and_b32_e32 v67, 0xffff0000, v64
	v_lshlrev_b32_e32 v64, 16, v65
	v_and_b32_e32 v65, 0xffff0000, v65
	v_pk_add_f32 v[26:27], v[26:27], v[66:67]
	v_pk_add_f32 v[28:29], v[28:29], v[64:65]
	v_mov_b32_e32 v66, v27
	v_mov_b32_e32 v67, v29
	v_mov_b32_e32 v64, v26
	v_mov_b32_e32 v65, v28
	v_pk_mul_f32 v[66:67], v[66:67], v[66:67]
	v_and_b32_e32 v79, 0xffff0000, v60
	v_pk_fma_f32 v[64:65], v[64:65], v[64:65], v[66:67]
	v_lshlrev_b32_e32 v66, 16, v62
	v_and_b32_e32 v67, 0xffff0000, v62
	v_lshlrev_b32_e32 v62, 16, v63
	v_and_b32_e32 v63, 0xffff0000, v63
	v_pk_add_f32 v[22:23], v[22:23], v[66:67]
	v_pk_add_f32 v[24:25], v[24:25], v[62:63]
	v_lshlrev_b32_e32 v60, 16, v61
	v_and_b32_e32 v61, 0xffff0000, v61
	v_mul_f32_e32 v62, v23, v23
	v_mul_f32_e32 v66, v25, v25
	v_pk_add_f32 v[18:19], v[18:19], v[78:79]
	v_pk_add_f32 v[20:21], v[20:21], v[60:61]
	v_pk_add_f32 v[30:31], v[30:31], v[30:31] op_sel:[0,1] op_sel_hi:[1,0]
	v_pk_add_f32 v[64:65], v[64:65], v[64:65] op_sel:[0,1] op_sel_hi:[1,0]
	v_pk_fma_f32 v[62:63], v[22:23], v[22:23], v[62:63] op_sel_hi:[1,1,0]
	v_pk_fma_f32 v[66:67], v[24:25], v[24:25], v[66:67] op_sel_hi:[1,1,0]
	v_pk_mul_f32 v[60:61], v[18:19], v[18:19]
	v_pk_mul_f32 v[78:79], v[20:21], v[20:21]
	v_mov_b32_e32 v31, v60
	v_mov_b32_e32 v65, v61
	v_mov_b32_e32 v63, v78
	v_mov_b32_e32 v67, v79
	v_pk_add_f32 v[30:31], v[30:31], v[64:65]
	v_pk_add_f32 v[60:61], v[62:63], v[66:67]
	s_nop 0
	v_pk_add_f32 v[30:31], v[30:31], v[60:61]
	v_mov_b64_e32 v[60:61], v[176:177]
	v_mov_b64_e32 v[62:63], v[178:179]
	v_mov_b64_e32 v[64:65], v[192:193]
	v_mov_b64_e32 v[66:67], v[194:195]
	v_add_f32_e32 v30, v30, v31
	v_pk_add_f32 v[62:63], v[62:63], 1.0 op_sel_hi:[1,0]
	s_nop 0
	v_add_f32_dpp v30, v30, v30 quad_perm:[1,0,3,2] row_mask:0xf bank_mask:0xf bound_ctrl:1
	v_pk_add_f32 v[60:61], v[60:61], 1.0 op_sel_hi:[1,0]
	s_nop 0
	v_add_f32_dpp v30, v30, v30 quad_perm:[2,3,0,1] row_mask:0xf bank_mask:0xf bound_ctrl:1
	s_nop 1
	v_add_f32_dpp v30, v30, v30 row_half_mirror row_mask:0xf bank_mask:0xf bound_ctrl:1
	s_nop 1
	v_add_f32_dpp v30, v30, v30 row_mirror row_mask:0xf bank_mask:0xf bound_ctrl:1
	s_nop 0
	v_readlane_b32 s8, v30, 16
	v_readlane_b32 s9, v30, 48
	v_readlane_b32 s2, v30, 0
	v_readlane_b32 s3, v30, 32
	v_mov_b32_e32 v30, s8
	v_mov_b32_e32 v31, s9
	v_pk_add_f32 v[30:31], s[2:3], v[30:31]
	s_nop 0
	v_add_f32_e32 v30, v30, v31
	v_fmamk_f32 v30, v30, 0x3a800000, v162
	v_cmp_gt_f32_e32 vcc, s82, v30
	v_mul_f32_e32 v31, 0x4b800000, v30
	s_nop 0
	v_cndmask_b32_e32 v30, v30, v31, vcc
	v_rsq_f32_e32 v30, v30
	s_nop 0
	v_mul_f32_e32 v31, 0x45800000, v30
	v_cndmask_b32_e32 v30, v30, v31, vcc
	v_pk_mul_f32 v[32:33], v[32:33], v[30:31] op_sel_hi:[1,0]
	v_pk_mul_f32 v[68:69], v[76:77], v[30:31] op_sel_hi:[1,0]
	v_pk_mul_f32 v[32:33], v[4:5], v[32:33]
	v_pk_mul_f32 v[68:69], v[2:3], v[68:69]
	v_pk_fma_f32 v[62:63], v[62:63], v[32:33], v[66:67]
	v_pk_fma_f32 v[32:33], v[60:61], v[68:69], v[64:65]
	v_pk_mul_f32 v[26:27], v[26:27], v[30:31] op_sel_hi:[1,0]
	v_cvt_pk_bf16_f32 v32, v32, v33
	v_cvt_pk_bf16_f32 v33, v62, v63
	global_store_dwordx2 v[54:55], v[32:33], off
	v_mov_b64_e32 v[60:61], v[180:181]
	v_mov_b64_e32 v[62:63], v[182:183]
	s_nop 0
	v_mov_b64_e32 v[56:57], v[196:197]
	v_mov_b64_e32 v[58:59], v[198:199]
	v_pk_mul_f32 v[28:29], v[28:29], v[30:31] op_sel_hi:[1,0]
	v_pk_mul_f32 v[26:27], v[6:7], v[26:27]
	v_pk_mul_f32 v[28:29], v[8:9], v[28:29]
	v_pk_mul_f32 v[22:23], v[22:23], v[30:31] op_sel_hi:[1,0]
	v_pk_mul_f32 v[24:25], v[24:25], v[30:31] op_sel_hi:[1,0]
	v_pk_mul_f32 v[22:23], v[10:11], v[22:23]
	v_pk_mul_f32 v[24:25], v[12:13], v[24:25]
	v_pk_mul_f32 v[18:19], v[18:19], v[30:31] op_sel_hi:[1,0]
	v_pk_mul_f32 v[20:21], v[20:21], v[30:31] op_sel_hi:[1,0]
	v_pk_mul_f32 v[18:19], v[14:15], v[18:19]
	v_cmp_lt_i32_e32 vcc, s34, v1
	v_pk_mul_f32 v[20:21], v[16:17], v[20:21]
	s_or_b64 s[12:13], vcc, s[12:13]
	v_pk_add_f32 v[60:61], v[60:61], 1.0 op_sel_hi:[1,0]
	v_pk_add_f32 v[32:33], v[62:63], 1.0 op_sel_hi:[1,0]
	v_pk_fma_f32 v[26:27], v[60:61], v[26:27], v[56:57]
	v_pk_fma_f32 v[28:29], v[32:33], v[28:29], v[58:59]
	v_cvt_pk_bf16_f32 v26, v26, v27
	s_nop 0
	v_cvt_pk_bf16_f32 v27, v28, v29
	global_store_dwordx2 v[54:55], v[26:27], off offset:512
	v_mov_b64_e32 v[26:27], v[184:185]
	v_mov_b64_e32 v[28:29], v[186:187]
	s_nop 0
	v_mov_b64_e32 v[32:33], v[200:201]
	v_mov_b64_e32 v[34:35], v[202:203]
	v_pk_add_f32 v[26:27], v[26:27], 1.0 op_sel_hi:[1,0]
	v_pk_add_f32 v[28:29], v[28:29], 1.0 op_sel_hi:[1,0]
	v_pk_fma_f32 v[22:23], v[26:27], v[22:23], v[32:33]
	v_pk_fma_f32 v[24:25], v[28:29], v[24:25], v[34:35]
	v_cvt_pk_bf16_f32 v22, v22, v23
	s_nop 0
	v_cvt_pk_bf16_f32 v23, v24, v25
	global_store_dwordx2 v[54:55], v[22:23], off offset:1024
	v_mov_b64_e32 v[22:23], v[188:189]
	v_mov_b64_e32 v[24:25], v[190:191]
	s_nop 0
	v_mov_b64_e32 v[26:27], v[204:205]
	v_mov_b64_e32 v[28:29], v[206:207]
	v_pk_add_f32 v[22:23], v[22:23], 1.0 op_sel_hi:[1,0]
	v_pk_add_f32 v[24:25], v[24:25], 1.0 op_sel_hi:[1,0]
	v_pk_fma_f32 v[18:19], v[18:19], v[22:23], v[26:27]
	v_pk_fma_f32 v[20:21], v[20:21], v[24:25], v[28:29]
	v_cvt_pk_bf16_f32 v18, v18, v19
	s_nop 0
	v_cvt_pk_bf16_f32 v19, v20, v21
	global_store_dwordx2 v[54:55], v[18:19], off offset:1536
	s_andn2_b64 exec, exec, s[12:13]
	s_cbranch_execnz .LBB0_253

.LBB0_398:
	s_or_b64 exec, exec, s[38:39]
	v_lshl_or_b32 v2, s8, 10, v142
	v_mov_b32_e32 v3, v0
	v_lshl_add_u64 v[2:3], v[68:69], 0, v[2:3]
	global_load_ushort v212, v[2:3], off
	global_load_ushort v213, v[2:3], off offset:1024
	global_load_ushort v214, v[2:3], off offset:2048
	global_load_ushort v215, v[2:3], off offset:3072
	v_add_u32_e32 v91, v143, v102
	ds_read_b128 v[92:95], v91 offset:12544
	ds_read_b128 v[164:167], v91 offset:13056
	ds_read_b128 v[216:219], v91 offset:13568
	ds_read_b128 v[220:223], v146 offset:12544
	ds_read_b128 v[224:227], v91 offset:14592
	ds_read_b128 v[228:231], v91 offset:15104
	ds_read_b128 v[244:247], v91 offset:15616
	ds_read_b128 v[248:251], v147 offset:12544
	v_add_u32_e32 v96, 0xf000, v138
	v_add_u32_e32 v97, 0xf400, v138
	v_add_u32_e32 v159, 0xf800, v138
	s_andn2_b64 vcc, exec, s[50:51]
	s_waitcnt lgkmcnt(7)
	v_mfma_f32_16x16x32_bf16 v[92:95], v[12:15], v[92:95], 0
	s_waitcnt lgkmcnt(6)
	v_mfma_f32_16x16x32_bf16 v[164:167], v[12:15], v[164:167], 0
	s_waitcnt lgkmcnt(5)
	v_mfma_f32_16x16x32_bf16 v[216:219], v[12:15], v[216:219], 0
	s_waitcnt lgkmcnt(4)
	v_mfma_f32_16x16x32_bf16 v[220:223], v[12:15], v[220:223], 0
	s_waitcnt lgkmcnt(3)
	v_mfma_f32_16x16x32_bf16 v[224:227], v[12:15], v[224:227], 0
	s_waitcnt lgkmcnt(2)
	v_mfma_f32_16x16x32_bf16 v[228:231], v[12:15], v[228:231], 0
	s_waitcnt lgkmcnt(1)
	v_mfma_f32_16x16x32_bf16 v[244:247], v[12:15], v[244:247], 0
	s_waitcnt lgkmcnt(0)
	v_mfma_f32_16x16x32_bf16 v[248:251], v[12:15], v[248:251], 0
	ds_write2_b32 v96, v92, v164 offset0:192 offset1:208
	ds_write2_b32 v97, v93, v165 offset0:64 offset1:80
	ds_write2_b32 v97, v94, v166 offset0:192 offset1:208
	ds_write2_b32 v159, v95, v167 offset0:64 offset1:80
	ds_write2_b32 v96, v216, v220 offset0:224 offset1:240
	ds_write2_b32 v97, v217, v221 offset0:96 offset1:112
	ds_write2_b32 v97, v218, v222 offset0:224 offset1:240
	ds_write2_b32 v159, v219, v223 offset0:96 offset1:112
	ds_write2_b32 v97, v224, v228 offset1:16
	ds_write2_b32 v97, v225, v229 offset0:128 offset1:144
	ds_write2_b32 v159, v226, v230 offset1:16
	ds_write2_b32 v159, v227, v231 offset0:128 offset1:144
	ds_write2_b32 v97, v244, v248 offset0:32 offset1:48
	ds_write2_b32 v97, v245, v249 offset0:160 offset1:176
	ds_write2_b32 v159, v246, v250 offset0:32 offset1:48
	ds_write2_b32 v159, v247, v251 offset0:160 offset1:176
	s_waitcnt lgkmcnt(0)
	ds_read2st64_b32 v[216:217], v140 offset1:1
	ds_read2st64_b32 v[218:219], v140 offset0:2 offset1:3
	ds_read2st64_b32 v[220:221], v140 offset0:4 offset1:5
	ds_read2st64_b32 v[222:223], v140 offset0:6 offset1:7
	ds_read2st64_b32 v[224:225], v140 offset0:8 offset1:9
	ds_read2st64_b32 v[226:227], v140 offset0:10 offset1:11
	ds_read2st64_b32 v[228:229], v140 offset0:12 offset1:13
	ds_read2st64_b32 v[230:231], v140 offset0:14 offset1:15
	ds_read2st64_b32 v[244:245], v140 offset0:16 offset1:17
	ds_read2st64_b32 v[246:247], v140 offset0:18 offset1:19
	ds_read2st64_b32 v[248:249], v140 offset0:20 offset1:21
	ds_read2st64_b32 v[250:251], v140 offset0:22 offset1:23
	ds_read2st64_b32 v[92:93], v140 offset0:24 offset1:25
	ds_read2st64_b32 v[94:95], v140 offset0:26 offset1:27
	ds_read2st64_b32 v[164:165], v140 offset0:28 offset1:29
	ds_read2st64_b32 v[166:167], v140 offset0:30 offset1:31
	s_waitcnt lgkmcnt(15)
	v_pk_fma_f32 v[14:15], v[64:65], v[60:61], v[216:217] op_sel:[0,1,0] op_sel_hi:[0,0,1] neg_lo:[1,0,0]
	v_pk_fma_f32 v[60:61], v[56:57], v[60:61], v[14:15] op_sel_hi:[0,1,1]
	v_cvt_pk_bf16_f32 v12, v60, v61
	ds_write_b16 v141, v12 offset:8192
	ds_write_b16_d16_hi v141, v12 offset:8320
	s_waitcnt lgkmcnt(15)
	v_pk_fma_f32 v[14:15], v[64:65], v[60:61], v[218:219] op_sel:[0,1,0] op_sel_hi:[0,0,1] neg_lo:[1,0,0]
	v_pk_fma_f32 v[60:61], v[56:57], v[60:61], v[14:15] op_sel_hi:[0,1,1]
	v_cvt_pk_bf16_f32 v13, v60, v61
	ds_write_b16 v141, v13 offset:8464
	ds_write_b16_d16_hi v141, v13 offset:8592
	s_waitcnt lgkmcnt(15)
	v_pk_fma_f32 v[14:15], v[64:65], v[60:61], v[220:221] op_sel:[0,1,0] op_sel_hi:[0,0,1] neg_lo:[1,0,0]
	v_pk_fma_f32 v[60:61], v[56:57], v[60:61], v[14:15] op_sel_hi:[0,1,1]
	v_cvt_pk_bf16_f32 v12, v60, v61
	ds_write_b16 v141, v12 offset:8736
	ds_write_b16_d16_hi v141, v12 offset:8864
	s_waitcnt lgkmcnt(15)
	v_pk_fma_f32 v[14:15], v[64:65], v[60:61], v[222:223] op_sel:[0,1,0] op_sel_hi:[0,0,1] neg_lo:[1,0,0]
	v_pk_fma_f32 v[60:61], v[56:57], v[60:61], v[14:15] op_sel_hi:[0,1,1]
	v_cvt_pk_bf16_f32 v13, v60, v61
	ds_write_b16 v141, v13 offset:9008
	ds_write_b16_d16_hi v141, v13 offset:9136
	s_waitcnt lgkmcnt(15)
	v_pk_fma_f32 v[14:15], v[64:65], v[60:61], v[224:225] op_sel:[0,1,0] op_sel_hi:[0,0,1] neg_lo:[1,0,0]
	v_pk_fma_f32 v[60:61], v[56:57], v[60:61], v[14:15] op_sel_hi:[0,1,1]
	v_cvt_pk_bf16_f32 v12, v60, v61
	ds_write_b16 v141, v12 offset:9280
	ds_write_b16_d16_hi v141, v12 offset:9408
	s_waitcnt lgkmcnt(15)
	v_pk_fma_f32 v[14:15], v[64:65], v[60:61], v[226:227] op_sel:[0,1,0] op_sel_hi:[0,0,1] neg_lo:[1,0,0]
	v_pk_fma_f32 v[60:61], v[56:57], v[60:61], v[14:15] op_sel_hi:[0,1,1]
	v_cvt_pk_bf16_f32 v13, v60, v61
	ds_write_b16 v141, v13 offset:9552
	ds_write_b16_d16_hi v141, v13 offset:9680
	s_waitcnt lgkmcnt(15)
	v_pk_fma_f32 v[14:15], v[64:65], v[60:61], v[228:229] op_sel:[0,1,0] op_sel_hi:[0,0,1] neg_lo:[1,0,0]
	v_pk_fma_f32 v[60:61], v[56:57], v[60:61], v[14:15] op_sel_hi:[0,1,1]
	v_cvt_pk_bf16_f32 v12, v60, v61
	ds_write_b16 v141, v12 offset:9824
	ds_write_b16_d16_hi v141, v12 offset:9952
	s_waitcnt lgkmcnt(15)
	v_pk_fma_f32 v[14:15], v[64:65], v[60:61], v[230:231] op_sel:[0,1,0] op_sel_hi:[0,0,1] neg_lo:[1,0,0]
	v_pk_fma_f32 v[60:61], v[56:57], v[60:61], v[14:15] op_sel_hi:[0,1,1]
	v_cvt_pk_bf16_f32 v13, v60, v61
	ds_write_b16 v141, v13 offset:10096
	ds_write_b16_d16_hi v141, v13 offset:10224
	s_waitcnt lgkmcnt(15)
	v_pk_fma_f32 v[14:15], v[64:65], v[60:61], v[244:245] op_sel:[0,1,0] op_sel_hi:[0,0,1] neg_lo:[1,0,0]
	v_pk_fma_f32 v[60:61], v[56:57], v[60:61], v[14:15] op_sel_hi:[0,1,1]
	v_cvt_pk_bf16_f32 v12, v60, v61
	ds_write_b16 v141, v12 offset:10368
	ds_write_b16_d16_hi v141, v12 offset:10496
	s_waitcnt lgkmcnt(15)
	v_pk_fma_f32 v[14:15], v[64:65], v[60:61], v[246:247] op_sel:[0,1,0] op_sel_hi:[0,0,1] neg_lo:[1,0,0]
	v_pk_fma_f32 v[60:61], v[56:57], v[60:61], v[14:15] op_sel_hi:[0,1,1]
	v_cvt_pk_bf16_f32 v13, v60, v61
	ds_write_b16 v141, v13 offset:10640
	ds_write_b16_d16_hi v141, v13 offset:10768
	s_waitcnt lgkmcnt(15)
	v_pk_fma_f32 v[14:15], v[64:65], v[60:61], v[248:249] op_sel:[0,1,0] op_sel_hi:[0,0,1] neg_lo:[1,0,0]
	v_pk_fma_f32 v[60:61], v[56:57], v[60:61], v[14:15] op_sel_hi:[0,1,1]
	v_cvt_pk_bf16_f32 v12, v60, v61
	ds_write_b16 v141, v12 offset:10912
	ds_write_b16_d16_hi v141, v12 offset:11040
	s_waitcnt lgkmcnt(15)
	v_pk_fma_f32 v[14:15], v[64:65], v[60:61], v[250:251] op_sel:[0,1,0] op_sel_hi:[0,0,1] neg_lo:[1,0,0]
	v_pk_fma_f32 v[60:61], v[56:57], v[60:61], v[14:15] op_sel_hi:[0,1,1]
	v_cvt_pk_bf16_f32 v13, v60, v61
	ds_write_b16 v141, v13 offset:11184
	ds_write_b16_d16_hi v141, v13 offset:11312
	s_waitcnt lgkmcnt(15)
	v_pk_fma_f32 v[14:15], v[64:65], v[60:61], v[92:93] op_sel:[0,1,0] op_sel_hi:[0,0,1] neg_lo:[1,0,0]
	v_pk_fma_f32 v[60:61], v[56:57], v[60:61], v[14:15] op_sel_hi:[0,1,1]
	v_cvt_pk_bf16_f32 v12, v60, v61
	ds_write_b16 v141, v12 offset:11456
	ds_write_b16_d16_hi v141, v12 offset:11584
	s_waitcnt lgkmcnt(15)
	v_pk_fma_f32 v[14:15], v[64:65], v[60:61], v[94:95] op_sel:[0,1,0] op_sel_hi:[0,0,1] neg_lo:[1,0,0]
	v_pk_fma_f32 v[60:61], v[56:57], v[60:61], v[14:15] op_sel_hi:[0,1,1]
	v_cvt_pk_bf16_f32 v13, v60, v61
	ds_write_b16 v141, v13 offset:11728
	ds_write_b16_d16_hi v141, v13 offset:11856
	s_waitcnt lgkmcnt(15)
	v_pk_fma_f32 v[14:15], v[64:65], v[60:61], v[164:165] op_sel:[0,1,0] op_sel_hi:[0,0,1] neg_lo:[1,0,0]
	v_pk_fma_f32 v[60:61], v[56:57], v[60:61], v[14:15] op_sel_hi:[0,1,1]
	v_cvt_pk_bf16_f32 v12, v60, v61
	ds_write_b16 v141, v12 offset:12000
	ds_write_b16_d16_hi v141, v12 offset:12128
	s_waitcnt lgkmcnt(15)
	v_pk_fma_f32 v[14:15], v[64:65], v[60:61], v[166:167] op_sel:[0,1,0] op_sel_hi:[0,0,1] neg_lo:[1,0,0]
	v_pk_fma_f32 v[60:61], v[56:57], v[60:61], v[14:15] op_sel_hi:[0,1,1]
	v_cvt_pk_bf16_f32 v13, v60, v61
	ds_write_b16 v141, v13 offset:12272
	ds_write_b16_d16_hi v141, v13 offset:12400
	s_waitcnt lgkmcnt(0)
	ds_read_b128 v[12:15], v144 offset:8192
	ds_read_b128 v[92:95], v145 offset:16640
	ds_read_b128 v[216:219], v144 offset:8256
	ds_read_b128 v[220:223], v145 offset:16704
	ds_read_b128 v[224:227], v144 offset:8320
	ds_read_b128 v[228:231], v145 offset:16768
	ds_read_b128 v[244:247], v144 offset:8384
	ds_read_b128 v[248:251], v145 offset:16832
	s_waitcnt lgkmcnt(6)
	v_mfma_f32_16x16x32_bf16 v[12:15], v[12:15], v[92:95], 0
	s_waitcnt lgkmcnt(4)
	v_mfma_f32_16x16x32_bf16 v[12:15], v[216:219], v[220:223], v[12:15]
	s_waitcnt lgkmcnt(2)
	v_mfma_f32_16x16x32_bf16 v[12:15], v[224:227], v[228:231], v[12:15]
	s_waitcnt lgkmcnt(0)
	v_mfma_f32_16x16x32_bf16 v[12:15], v[244:247], v[248:251], v[12:15]
	s_nop 7
	s_waitcnt vmcnt(0)
	v_lshlrev_b32_e32 v88, 16, v212
	v_lshlrev_b32_e32 v89, 16, v213
	v_lshlrev_b32_e32 v90, 16, v214
	v_lshlrev_b32_e32 v91, 16, v215
	v_pk_fma_f32 v[12:13], v[148:149], v[88:89], v[12:13] op_sel_hi:[0,1,1]
	v_pk_fma_f32 v[14:15], v[148:149], v[90:91], v[14:15] op_sel_hi:[0,1,1]
	v_mov_b32_e32 v88, 0x3dd2d3e8
	v_mov_b32_e32 v90, 0x40135761
	v_pk_mul_f32 v[92:93], v[12:13], v[12:13]
	v_pk_mul_f32 v[94:95], v[14:15], v[14:15]
	v_pk_fma_f32 v[92:93], v[92:93], v[88:89], v[90:91] op_sel_hi:[1,0,0]
	v_pk_fma_f32 v[94:95], v[94:95], v[88:89], v[90:91] op_sel_hi:[1,0,0]
	v_pk_mul_f32 v[92:93], v[92:93], v[12:13]
	v_pk_mul_f32 v[94:95], v[94:95], v[14:15]
	v_mov_b32_e32 v88, 1.0
	v_exp_f32_e32 v92, v92
	v_exp_f32_e32 v93, v93
	v_exp_f32_e32 v94, v94
	v_exp_f32_e32 v95, v95
	s_nop 0
	v_pk_add_f32 v[92:93], v[92:93], v[88:89] op_sel_hi:[1,0]
	v_pk_add_f32 v[94:95], v[94:95], v[88:89] op_sel_hi:[1,0]
	v_rcp_f32_e32 v92, v92
	v_rcp_f32_e32 v93, v93
	v_rcp_f32_e32 v94, v94
	v_rcp_f32_e32 v95, v95
	s_nop 0
	v_pk_fma_f32 v[12:13], v[12:13], v[92:93], v[12:13] neg_lo:[1,0,0] neg_hi:[1,0,0]
	v_pk_fma_f32 v[14:15], v[14:15], v[94:95], v[14:15] neg_lo:[1,0,0] neg_hi:[1,0,0]
	v_cvt_pk_bf16_f32 v12, v12, v13
	v_cvt_pk_bf16_f32 v14, v14, v15
	global_store_short v[2:3], v12, off
	global_store_short_d16_hi v[2:3], v12, off offset:1024
	global_store_short v[2:3], v14, off offset:2048
	global_store_short_d16_hi v[2:3], v14, off offset:3072
	s_waitcnt lgkmcnt(0)
	v_lshlrev_b32_e32 v1, 2, v128
	s_cbranch_vccnz .LBB0_408
	s_waitcnt vmcnt(4)
	v_lshlrev_b32_e32 v16, 16, v176
	v_lshlrev_b32_e32 v30, 16, v177
	v_lshlrev_b32_e32 v32, 16, v178
	v_lshlrev_b32_e32 v36, 16, v179
	v_lshlrev_b32_e32 v17, 16, v180
	v_lshlrev_b32_e32 v26, 16, v181
	v_lshlrev_b32_e32 v27, 16, v182
	v_lshlrev_b32_e32 v28, 16, v183
	v_lshlrev_b32_e32 v29, 16, v184
	v_lshlrev_b32_e32 v31, 16, v185
	v_lshlrev_b32_e32 v33, 16, v186
	v_lshlrev_b32_e32 v37, 16, v187
	v_lshlrev_b32_e32 v34, 16, v188
	v_lshlrev_b32_e32 v35, 16, v189
	v_lshlrev_b32_e32 v38, 16, v190
	v_lshlrev_b32_e32 v39, 16, v195
	v_lshlrev_b32_e32 v40, 16, v197
	v_lshlrev_b32_e32 v43, 16, v198
	v_lshlrev_b32_e32 v42, 16, v199
	v_lshlrev_b32_e32 v45, 16, v200
	v_lshlrev_b32_e32 v44, 16, v201
	v_lshlrev_b32_e32 v46, 16, v203
	v_lshlrev_b32_e32 v49, 16, v204
	v_lshlrev_b32_e32 v48, 16, v205
	v_lshlrev_b32_e32 v41, 16, v196
	v_lshlrev_b32_e32 v47, 16, v202
	v_lshlrev_b32_e32 v51, 16, v206
	v_lshlrev_b32_e32 v50, 16, v207
	v_lshlrev_b32_e32 v53, 16, v191
	v_lshlrev_b32_e32 v52, 16, v193
	v_lshlrev_b32_e32 v55, 16, v192
	v_lshlrev_b32_e32 v54, 16, v194
	v_add_f32_e32 v88, v155, v35
	v_mul_f32_e32 v88, 0xbfb8aa3b, v88
	v_exp_f32_e32 v88, v88
	v_pk_add_f32 v[12:13], v[32:33], v[26:27] neg_lo:[0,1] neg_hi:[0,1]
	v_pk_add_f32 v[2:3], v[30:31], v[16:17] neg_lo:[0,1] neg_hi:[0,1]
	v_fma_f32 v13, v150, v13, v27
	v_add_f32_e32 v88, 1.0, v88
	v_rcp_f32_e32 v88, v88
	v_mul_f32_e32 v92, v157, v13
	v_fma_f32 v3, v149, v3, v17
	s_bitcmp1_b32 s3, 0
	v_mul_f32_e32 v89, 0xbf6002b1, v88
	v_cmp_gt_f32_e32 vcc, s85, v89
	s_cselect_b32 s8, 0x5000, 0
	v_mov_b32_e32 v94, v0
	v_cndmask_b32_e32 v89, 0, v239, vcc
	v_fmac_f32_e32 v89, 0xbf6002b1, v88
	v_exp_f32_e32 v88, v89
	v_cndmask_b32_e32 v89, 0, v236, vcc
	s_add_i32 s9, s8, 0
	s_mul_i32 s8, s3, 0xab
	v_ldexp_f32 v90, v88, v89
	v_add_f32_e32 v88, v154, v39
	v_mul_f32_e32 v88, 0xbfb8aa3b, v88
	v_exp_f32_e32 v88, v88
	v_mov_b32_e32 v89, v0
	s_bfe_u32 s8, s8, 0x70009
	s_mul_i32 s8, s8, 3
	v_add_f32_e32 v88, 1.0, v88
	v_rcp_f32_e32 v91, v88
	v_mul_f32_e32 v88, v92, v92
	s_sub_i32 s8, s3, s8
	s_and_b32 s8, s8, 0xff
	v_mov_b32_dpp v89, v88 quad_perm:[1,0,3,2] row_mask:0xf bank_mask:0xf
	v_fmac_f32_e32 v89, v92, v92
	s_mulk_i32 s8, 0x1100
	s_add_i32 s8, s8, 0
	v_add_f32_dpp v88, v89, v89 quad_perm:[2,3,0,1] row_mask:0xf bank_mask:0xf bound_ctrl:1
	v_pk_add_f32 v[14:15], v[36:37], v[28:29] neg_lo:[0,1] neg_hi:[0,1]
	s_nop 0
	v_add_f32_dpp v88, v88, v88 row_half_mirror row_mask:0xf bank_mask:0xf bound_ctrl:1
	v_fma_f32 v15, v151, v15, v29
	s_nop 0
	v_add_f32_dpp v88, v88, v88 row_mirror row_mask:0xf bank_mask:0xf bound_ctrl:1
	s_nop 0
	s_nop 1
	v_add_f32_dpp v88, v88, v88 row_bcast:15 row_mask:0xa bank_mask:0xf
	s_nop 1
	v_add_f32_dpp v88, v88, v88 row_bcast:31 row_mask:0xc bank_mask:0xf
	s_nop 0
	v_readlane_b32 s26, v88, 63
	s_nop 1
	v_mov_b32_e32 v88, s26
	v_add_f32_e32 v88, 0x2b8cbccc, v88
	v_cmp_gt_f32_e32 vcc, s82, v88
	v_mul_f32_e32 v89, 0x4b800000, v88
	s_nop 0
	v_cndmask_b32_e32 v88, v88, v89, vcc
	v_rsq_f32_e32 v88, v88
	s_nop 0
	v_mul_f32_e32 v89, 0x45800000, v88
	v_cndmask_b32_e32 v88, v88, v89, vcc
	v_add_f32_e32 v89, -1.0, v91
	v_fma_f32 v89, v158, v89, 1.0
	v_mul_f32_e32 v13, v89, v13
	v_mul_f32_e32 v89, v13, v3
	v_mul_f32_e32 v93, v156, v89
	v_mul_f32_e64 v88, v92, -v88
	s_nop 0
	v_mov_b32_dpp v94, v93 quad_perm:[1,0,3,2] row_mask:0xf bank_mask:0xf
	v_fmac_f32_e32 v94, v156, v89
	s_nop 1
	v_add_f32_dpp v89, v94, v94 quad_perm:[2,3,0,1] row_mask:0xf bank_mask:0xf bound_ctrl:1
	s_nop 1
	v_add_f32_dpp v89, v89, v89 row_half_mirror row_mask:0xf bank_mask:0xf bound_ctrl:1
	s_nop 1
	v_add_f32_dpp v89, v89, v89 row_mirror row_mask:0xf bank_mask:0xf bound_ctrl:1
	s_nop 0
	s_nop 1
	v_add_f32_dpp v89, v89, v89 row_bcast:15 row_mask:0xa bank_mask:0xf
	s_nop 1
	v_add_f32_dpp v89, v89, v89 row_bcast:31 row_mask:0xc bank_mask:0xf
	s_nop 0
	v_readlane_b32 s38, v89, 63
	v_add_u32_e32 v89, s9, v1
	ds_write2st64_b32 v89, v90, v88 offset1:16
	v_mul_f32_e64 v88, v91, -v88
	ds_write2st64_b32 v89, v88, v13 offset0:32 offset1:48
	ds_write_b32 v89, v3 offset:16384
	v_add_u32_e32 v3, s8, v1
	ds_write_b32 v3, v15 offset:40960
	s_and_saveexec_b64 s[50:51], s[44:45]
	s_cbranch_execz .LBB0_401
	s_lshl_b32 s24, s96, 2
	s_add_i32 s24, s8, s24
	v_mov_b32_e32 v13, s24
	v_mov_b32_e32 v3, s38
	ds_write_b32 v13, v3 offset:45056
.LBB0_401:
	s_or_b64 exec, exec, s[50:51]
	v_fma_f32 v13, v149, v2, v16
	v_add_f32_e32 v2, v155, v34
	v_mul_f32_e32 v2, 0xbfb8aa3b, v2
	v_exp_f32_e32 v2, v2
	v_fma_f32 v12, v150, v12, v26
	v_mul_f32_e32 v89, v157, v12
	v_mov_b32_e32 v91, v0
	v_add_f32_e32 v2, 1.0, v2
	v_rcp_f32_e32 v2, v2
	v_fma_f32 v14, v151, v14, v28
	v_mul_f32_e32 v3, 0xbf6002b1, v2
	v_cmp_gt_f32_e32 vcc, s85, v3
	s_nop 1
	v_cndmask_b32_e32 v3, 0, v239, vcc
	v_fmac_f32_e32 v3, 0xbf6002b1, v2
	v_exp_f32_e32 v2, v3
	v_cndmask_b32_e32 v3, 0, v236, vcc
	v_ldexp_f32 v15, v2, v3
	v_add_f32_e32 v2, v154, v38
	v_mul_f32_e32 v2, 0xbfb8aa3b, v2
	v_exp_f32_e32 v2, v2
	v_mov_b32_e32 v3, v0
	v_add_f32_e32 v2, 1.0, v2
	v_rcp_f32_e32 v88, v2
	v_mul_f32_e32 v2, v89, v89
	s_nop 1
	v_mov_b32_dpp v3, v2 quad_perm:[1,0,3,2] row_mask:0xf bank_mask:0xf
	v_fmac_f32_e32 v3, v89, v89
	s_nop 1
	v_add_f32_dpp v2, v3, v3 quad_perm:[2,3,0,1] row_mask:0xf bank_mask:0xf bound_ctrl:1
	s_nop 1
	v_add_f32_dpp v2, v2, v2 row_half_mirror row_mask:0xf bank_mask:0xf bound_ctrl:1
	s_nop 1
	v_add_f32_dpp v2, v2, v2 row_mirror row_mask:0xf bank_mask:0xf bound_ctrl:1
	s_nop 0
	s_nop 1
	v_add_f32_dpp v2, v2, v2 row_bcast:15 row_mask:0xa bank_mask:0xf
	s_nop 1
	v_add_f32_dpp v2, v2, v2 row_bcast:31 row_mask:0xc bank_mask:0xf
	s_nop 0
	v_readlane_b32 s26, v2, 63
	s_nop 1
	v_mov_b32_e32 v2, s26
	v_add_f32_e32 v2, 0x2b8cbccc, v2
	v_cmp_gt_f32_e32 vcc, s82, v2
	v_mul_f32_e32 v3, 0x4b800000, v2
	s_nop 0
	v_cndmask_b32_e32 v2, v2, v3, vcc
	v_rsq_f32_e32 v2, v2
	s_nop 0
	v_mul_f32_e32 v3, 0x45800000, v2
	v_cndmask_b32_e32 v2, v2, v3, vcc
	v_add_f32_e32 v3, -1.0, v88
	v_fma_f32 v3, v158, v3, 1.0
	v_mul_f32_e32 v3, v3, v12
	v_mul_f32_e32 v12, v3, v13
	v_mul_f32_e32 v90, v156, v12
	v_mul_f32_e64 v2, v89, -v2
	s_nop 0
	v_mov_b32_dpp v91, v90 quad_perm:[1,0,3,2] row_mask:0xf bank_mask:0xf
	v_fmac_f32_e32 v91, v156, v12
	s_nop 1
	v_add_f32_dpp v12, v91, v91 quad_perm:[2,3,0,1] row_mask:0xf bank_mask:0xf bound_ctrl:1
	s_nop 1
	v_add_f32_dpp v12, v12, v12 row_half_mirror row_mask:0xf bank_mask:0xf bound_ctrl:1
	s_nop 1
	v_add_f32_dpp v12, v12, v12 row_mirror row_mask:0xf bank_mask:0xf bound_ctrl:1
	s_nop 0
	s_nop 1
	v_add_f32_dpp v12, v12, v12 row_bcast:15 row_mask:0xa bank_mask:0xf
	s_nop 1
	v_add_f32_dpp v12, v12, v12 row_bcast:31 row_mask:0xc bank_mask:0xf
	s_nop 0
	v_readlane_b32 s38, v12, 63
	v_lshlrev_b32_e32 v12, 2, v130
	v_add_u32_e32 v90, s9, v12
	ds_write2st64_b32 v90, v15, v2 offset1:16
	v_mul_f32_e64 v2, v88, -v2
	ds_write2st64_b32 v90, v2, v3 offset0:32 offset1:48
	ds_write_b32 v90, v13 offset:16384
	v_add_u32_e32 v2, s8, v12
	ds_write_b32 v2, v14 offset:40960
	s_and_saveexec_b64 s[50:51], s[44:45]
	s_cbranch_execz .LBB0_403
	s_lshl_b32 s24, s96, 2
	s_add_i32 s24, s8, s24
	s_nop 0
	v_mov_b32_e32 v2, s38
	v_mov_b32_e32 v3, s24
	ds_write_b32 v3, v2 offset:45072
.LBB0_403:
	s_or_b64 exec, exec, s[50:51]
	v_add_f32_e32 v88, v155, v53
	v_mul_f32_e32 v88, 0xbfb8aa3b, v88
	v_exp_f32_e32 v88, v88
	v_pk_add_f32 v[12:13], v[48:49], v[42:43] neg_lo:[0,1] neg_hi:[0,1]
	v_pk_add_f32 v[2:3], v[46:47], v[40:41] neg_lo:[0,1] neg_hi:[0,1]
	v_fma_f32 v13, v150, v13, v43
	v_add_f32_e32 v88, 1.0, v88
	v_rcp_f32_e32 v88, v88
	v_mul_f32_e32 v92, v157, v13
	v_fma_f32 v3, v149, v3, v41
	v_mov_b32_e32 v94, v0
	v_mul_f32_e32 v89, 0xbf6002b1, v88
	v_cmp_gt_f32_e32 vcc, s85, v89
	v_pk_add_f32 v[14:15], v[50:51], v[44:45] neg_lo:[0,1] neg_hi:[0,1]
	s_nop 0
	v_cndmask_b32_e32 v89, 0, v239, vcc
	v_fmac_f32_e32 v89, 0xbf6002b1, v88
	v_exp_f32_e32 v88, v89
	v_cndmask_b32_e32 v89, 0, v236, vcc
	v_fma_f32 v15, v151, v15, v45
	v_ldexp_f32 v90, v88, v89
	v_add_f32_e32 v88, v154, v55
	v_mul_f32_e32 v88, 0xbfb8aa3b, v88
	v_exp_f32_e32 v88, v88
	v_mov_b32_e32 v89, v0
	v_add_f32_e32 v88, 1.0, v88
	v_rcp_f32_e32 v91, v88
	v_mul_f32_e32 v88, v92, v92
	s_nop 1
	v_mov_b32_dpp v89, v88 quad_perm:[1,0,3,2] row_mask:0xf bank_mask:0xf
	v_fmac_f32_e32 v89, v92, v92
	s_nop 1
	v_add_f32_dpp v88, v89, v89 quad_perm:[2,3,0,1] row_mask:0xf bank_mask:0xf bound_ctrl:1
	s_nop 1
	v_add_f32_dpp v88, v88, v88 row_half_mirror row_mask:0xf bank_mask:0xf bound_ctrl:1
	s_nop 1
	v_add_f32_dpp v88, v88, v88 row_mirror row_mask:0xf bank_mask:0xf bound_ctrl:1
	s_nop 0
	s_nop 1
	v_add_f32_dpp v88, v88, v88 row_bcast:15 row_mask:0xa bank_mask:0xf
	s_nop 1
	v_add_f32_dpp v88, v88, v88 row_bcast:31 row_mask:0xc bank_mask:0xf
	s_nop 0
	v_readlane_b32 s26, v88, 63
	s_nop 1
	v_mov_b32_e32 v88, s26
	v_add_f32_e32 v88, 0x2b8cbccc, v88
	v_cmp_gt_f32_e32 vcc, s82, v88
	v_mul_f32_e32 v89, 0x4b800000, v88
	s_nop 0
	v_cndmask_b32_e32 v88, v88, v89, vcc
	v_rsq_f32_e32 v88, v88
	s_nop 0
	v_mul_f32_e32 v89, 0x45800000, v88
	v_cndmask_b32_e32 v88, v88, v89, vcc
	v_add_f32_e32 v89, -1.0, v91
	v_fma_f32 v89, v158, v89, 1.0
	v_mul_f32_e32 v13, v89, v13
	v_mul_f32_e32 v89, v13, v3
	v_mul_f32_e32 v93, v156, v89
	v_mul_f32_e64 v88, v92, -v88
	s_nop 0
	v_mov_b32_dpp v94, v93 quad_perm:[1,0,3,2] row_mask:0xf bank_mask:0xf
	v_fmac_f32_e32 v94, v156, v89
	s_nop 1
	v_add_f32_dpp v89, v94, v94 quad_perm:[2,3,0,1] row_mask:0xf bank_mask:0xf bound_ctrl:1
	s_nop 1
	v_add_f32_dpp v89, v89, v89 row_half_mirror row_mask:0xf bank_mask:0xf bound_ctrl:1
	s_nop 1
	v_add_f32_dpp v89, v89, v89 row_mirror row_mask:0xf bank_mask:0xf bound_ctrl:1
	s_nop 0
	s_nop 1
	v_add_f32_dpp v89, v89, v89 row_bcast:15 row_mask:0xa bank_mask:0xf
	s_nop 1
	v_add_f32_dpp v89, v89, v89 row_bcast:31 row_mask:0xc bank_mask:0xf
	s_nop 0
	v_readlane_b32 s38, v89, 63
	v_lshlrev_b32_e32 v89, 2, v132
	v_add_u32_e32 v93, s9, v89
	ds_write2st64_b32 v93, v90, v88 offset1:16
	v_mul_f32_e64 v88, v91, -v88
	ds_write2st64_b32 v93, v88, v13 offset0:32 offset1:48
	ds_write_b32 v93, v3 offset:16384
	v_add_u32_e32 v3, s8, v89
	ds_write_b32 v3, v15 offset:40960
	s_and_saveexec_b64 s[50:51], s[44:45]
	s_cbranch_execz .LBB0_405
	s_lshl_b32 s24, s96, 2
	s_add_i32 s24, s8, s24
	v_mov_b32_e32 v13, s24
	v_mov_b32_e32 v3, s38
	ds_write_b32 v13, v3 offset:45088
.LBB0_405:
	s_or_b64 exec, exec, s[50:51]
	v_fma_f32 v13, v149, v2, v40
	v_add_f32_e32 v2, v155, v52
	v_mul_f32_e32 v2, 0xbfb8aa3b, v2
	v_exp_f32_e32 v2, v2
	v_fma_f32 v12, v150, v12, v42
	v_mul_f32_e32 v89, v157, v12
	v_mov_b32_e32 v91, v0
	v_add_f32_e32 v2, 1.0, v2
	v_rcp_f32_e32 v2, v2
	v_fma_f32 v14, v151, v14, v44
	v_mul_f32_e32 v3, 0xbf6002b1, v2
	v_cmp_gt_f32_e32 vcc, s85, v3
	s_nop 1
	v_cndmask_b32_e32 v3, 0, v239, vcc
	v_fmac_f32_e32 v3, 0xbf6002b1, v2
	v_exp_f32_e32 v2, v3
	v_cndmask_b32_e32 v3, 0, v236, vcc
	v_ldexp_f32 v15, v2, v3
	v_add_f32_e32 v2, v154, v54
	v_mul_f32_e32 v2, 0xbfb8aa3b, v2
	v_exp_f32_e32 v2, v2
	v_mov_b32_e32 v3, v0
	v_add_f32_e32 v2, 1.0, v2
	v_rcp_f32_e32 v88, v2
	v_mul_f32_e32 v2, v89, v89
	s_nop 1
	v_mov_b32_dpp v3, v2 quad_perm:[1,0,3,2] row_mask:0xf bank_mask:0xf
	v_fmac_f32_e32 v3, v89, v89
	s_nop 1
	v_add_f32_dpp v2, v3, v3 quad_perm:[2,3,0,1] row_mask:0xf bank_mask:0xf bound_ctrl:1
	s_nop 1
	v_add_f32_dpp v2, v2, v2 row_half_mirror row_mask:0xf bank_mask:0xf bound_ctrl:1
	s_nop 1
	v_add_f32_dpp v2, v2, v2 row_mirror row_mask:0xf bank_mask:0xf bound_ctrl:1
	s_nop 0
	s_nop 1
	v_add_f32_dpp v2, v2, v2 row_bcast:15 row_mask:0xa bank_mask:0xf
	s_nop 1
	v_add_f32_dpp v2, v2, v2 row_bcast:31 row_mask:0xc bank_mask:0xf
	s_nop 0
	v_readlane_b32 s26, v2, 63
	s_nop 1
	v_mov_b32_e32 v2, s26
	v_add_f32_e32 v2, 0x2b8cbccc, v2
	v_cmp_gt_f32_e32 vcc, s82, v2
	v_mul_f32_e32 v3, 0x4b800000, v2
	s_nop 0
	v_cndmask_b32_e32 v2, v2, v3, vcc
	v_rsq_f32_e32 v2, v2
	s_nop 0
	v_mul_f32_e32 v3, 0x45800000, v2
	v_cndmask_b32_e32 v2, v2, v3, vcc
	v_add_f32_e32 v3, -1.0, v88
	v_fma_f32 v3, v158, v3, 1.0
	v_mul_f32_e32 v3, v3, v12
	v_mul_f32_e32 v12, v3, v13
	v_mul_f32_e32 v90, v156, v12
	v_mul_f32_e64 v2, v89, -v2
	s_nop 0
	v_mov_b32_dpp v91, v90 quad_perm:[1,0,3,2] row_mask:0xf bank_mask:0xf
	v_fmac_f32_e32 v91, v156, v12
	s_nop 1
	v_add_f32_dpp v12, v91, v91 quad_perm:[2,3,0,1] row_mask:0xf bank_mask:0xf bound_ctrl:1
	s_nop 1
	v_add_f32_dpp v12, v12, v12 row_half_mirror row_mask:0xf bank_mask:0xf bound_ctrl:1
	s_nop 1
	v_add_f32_dpp v12, v12, v12 row_mirror row_mask:0xf bank_mask:0xf bound_ctrl:1
	s_nop 0
	s_nop 1
	v_add_f32_dpp v12, v12, v12 row_bcast:15 row_mask:0xa bank_mask:0xf
	s_nop 1
	v_add_f32_dpp v12, v12, v12 row_bcast:31 row_mask:0xc bank_mask:0xf
	s_nop 0
	v_readlane_b32 s38, v12, 63
	v_lshlrev_b32_e32 v12, 2, v134
	v_add_u32_e32 v90, s9, v12
	ds_write2st64_b32 v90, v15, v2 offset1:16
	v_mul_f32_e64 v2, v88, -v2
	ds_write2st64_b32 v90, v2, v3 offset0:32 offset1:48
	ds_write_b32 v90, v13 offset:16384
	v_add_u32_e32 v2, s8, v12
	ds_write_b32 v2, v14 offset:40960
	s_and_saveexec_b64 s[50:51], s[44:45]
	s_cbranch_execz .LBB0_407
	s_lshl_b32 s9, s96, 2
	s_add_i32 s8, s8, s9
	s_nop 0
	v_mov_b32_e32 v2, s38
	v_mov_b32_e32 v3, s8
	ds_write_b32 v3, v2 offset:45104

.LBB0_408:
	s_andn2_b64 vcc, exec, s[36:37]
	s_mov_b32 s8, 1
	s_cbranch_vccnz .LBB0_410
	s_waitcnt vmcnt(4)
	v_lshlrev_b32_e32 v4, 16, v208
	v_lshlrev_b32_e32 v5, 16, v209
	v_lshlrev_b32_e32 v6, 16, v210
	v_lshlrev_b32_e32 v7, 16, v211
	s_add_i32 s8, s2, -1
	s_and_b32 s2, s8, 0xff
	s_mulk_i32 s2, 0xab
	s_lshr_b32 s2, s2, 9
	s_mul_i32 s2, s2, 3
	s_sub_i32 s2, s8, s2
	s_and_b32 s2, s2, 0xff
	s_lshl_b32 s9, s8, 12
	s_mulk_i32 s2, 0x1100
	s_and_b32 s9, s9, 0x1000
	s_add_i32 s2, s2, 0
	s_add_i32 s9, s9, 0
	v_lshlrev_b32_e32 v15, 2, v134
	v_add_u32_e32 v2, s9, v1
	v_add_u32_e32 v1, s2, v1
	v_lshlrev_b32_e32 v3, 2, v130
	v_lshlrev_b32_e32 v13, 2, v132
	v_add_u32_e32 v88, s9, v15
	v_add_u32_e32 v12, s9, v3
	v_add_u32_e32 v3, s2, v3
	v_add_u32_e32 v14, s9, v13
	v_add_u32_e32 v13, s2, v13
	v_add_u32_e32 v15, s2, v15
	ds_read_b32 v89, v2 offset:54016
	ds_read_b32 v1, v1 offset:40960
	ds_read_b32 v90, v12 offset:54016
	ds_read_b32 v91, v3 offset:40960
	ds_read_b32 v92, v14 offset:54016
	ds_read_b32 v93, v13 offset:40960
	ds_read_b32 v88, v88 offset:54016
	ds_read_b32 v94, v15 offset:40960
	s_waitcnt lgkmcnt(7)
	v_add_f32_dpp v2, v89, v89 quad_perm:[1,0,3,2] row_mask:0xf bank_mask:0xf bound_ctrl:1
	s_lshl_b32 s8, s8, 4
	s_add_u32 s36, s30, s8
	v_add_f32_dpp v2, v2, v2 quad_perm:[2,3,0,1] row_mask:0xf bank_mask:0xf bound_ctrl:1
	s_addc_u32 s37, s31, 0
	s_nop 0
	v_add_f32_dpp v2, v2, v2 row_half_mirror row_mask:0xf bank_mask:0xf bound_ctrl:1
	s_nop 1
	v_add_f32_dpp v2, v2, v2 row_mirror row_mask:0xf bank_mask:0xf bound_ctrl:1
	s_nop 0
	s_nop 1
	v_add_f32_dpp v2, v2, v2 row_bcast:15 row_mask:0xa bank_mask:0xf
	s_nop 1
	v_add_f32_dpp v2, v2, v2 row_bcast:31 row_mask:0xc bank_mask:0xf
	s_nop 0
	v_readlane_b32 s9, v2, 63
	s_nop 1
	v_mov_b32_e32 v2, s9
	v_fmac_f32_e32 v89, 0xbc800000, v2
	v_mul_f32_e32 v2, v89, v89
	v_mov_b32_e32 v3, v0
	s_nop 1
	v_mov_b32_dpp v3, v2 quad_perm:[1,0,3,2] row_mask:0xf bank_mask:0xf
	v_fmac_f32_e32 v3, v89, v89
	s_nop 1
	v_add_f32_dpp v2, v3, v3 quad_perm:[2,3,0,1] row_mask:0xf bank_mask:0xf bound_ctrl:1
	s_nop 1
	v_add_f32_dpp v2, v2, v2 row_half_mirror row_mask:0xf bank_mask:0xf bound_ctrl:1
	s_nop 1
	v_add_f32_dpp v2, v2, v2 row_mirror row_mask:0xf bank_mask:0xf bound_ctrl:1
	s_nop 0
	s_lshl_b32 s24, s96, 2
	s_nop 1
	v_add_f32_dpp v2, v2, v2 row_bcast:15 row_mask:0xa bank_mask:0xf
	s_nop 1
	v_add_f32_dpp v2, v2, v2 row_bcast:31 row_mask:0xc bank_mask:0xf
	s_nop 0
	v_readlane_b32 s9, v2, 63
	s_nop 1
	v_mov_b32_e32 v2, s9
	v_fmamk_f32 v2, v2, 0x3c800000, v233
	v_mul_f32_e32 v3, 0x4b800000, v2
	v_cmp_gt_f32_e32 vcc, s82, v2
	s_add_i32 s2, s2, s24
	s_or_b64 s[8:9], s[36:37], s[96:97]
	v_cndmask_b32_e32 v2, v2, v3, vcc
	v_rsq_f32_e32 v12, v2
	v_mov_b32_e32 v2, s2
	v_add_u32_e32 v14, 0xb000, v2
	ds_read2_b32 v[2:3], v14 offset1:4
	v_mul_f32_e32 v13, 0x45800000, v12
	v_cndmask_b32_e32 v12, v12, v13, vcc
	v_mul_f32_e32 v12, v89, v12
	v_fma_f32 v15, v153, v12, v152
	s_waitcnt lgkmcnt(0)
	v_fmac_f32_e32 v15, v2, v1
	v_add_f32_dpp v2, v90, v90 quad_perm:[1,0,3,2] row_mask:0xf bank_mask:0xf bound_ctrl:1
	ds_read2_b32 v[12:13], v14 offset0:8 offset1:12
	v_mul_f32_e32 v1, v4, v15
	v_add_f32_dpp v2, v2, v2 quad_perm:[2,3,0,1] row_mask:0xf bank_mask:0xf bound_ctrl:1
	s_lshl_b64 s[8:9], s[8:9], 10
	v_cvt_pk_bf16_f32 v1, v1, v0
	s_nop 0
	v_add_f32_dpp v2, v2, v2 row_half_mirror row_mask:0xf bank_mask:0xf bound_ctrl:1
	s_nop 1
	v_add_f32_dpp v2, v2, v2 row_mirror row_mask:0xf bank_mask:0xf bound_ctrl:1
	s_nop 0
	s_nop 1
	v_add_f32_dpp v2, v2, v2 row_bcast:15 row_mask:0xa bank_mask:0xf
	s_nop 1
	v_add_f32_dpp v2, v2, v2 row_bcast:31 row_mask:0xc bank_mask:0xf
	s_nop 0
	v_readlane_b32 s2, v2, 63
	s_nop 1
	v_mov_b32_e32 v2, s2
	v_fmac_f32_e32 v90, 0xbc800000, v2
	v_mul_f32_e32 v2, v90, v90
	v_mov_b32_e32 v14, v0
	s_nop 1
	v_mov_b32_dpp v14, v2 quad_perm:[1,0,3,2] row_mask:0xf bank_mask:0xf
	v_fmac_f32_e32 v14, v90, v90
	s_nop 1
	v_add_f32_dpp v2, v14, v14 quad_perm:[2,3,0,1] row_mask:0xf bank_mask:0xf bound_ctrl:1
	s_nop 1
	v_add_f32_dpp v2, v2, v2 row_half_mirror row_mask:0xf bank_mask:0xf bound_ctrl:1
	s_nop 1
	v_add_f32_dpp v2, v2, v2 row_mirror row_mask:0xf bank_mask:0xf bound_ctrl:1
	s_nop 0
	s_nop 1
	v_add_f32_dpp v2, v2, v2 row_bcast:15 row_mask:0xa bank_mask:0xf
	s_nop 1
	v_add_f32_dpp v2, v2, v2 row_bcast:31 row_mask:0xc bank_mask:0xf
	s_nop 0
	v_readlane_b32 s2, v2, 63
	s_nop 1
	v_mov_b32_e32 v2, s2
	v_fmamk_f32 v2, v2, 0x3c800000, v233
	v_mul_f32_e32 v14, 0x4b800000, v2
	v_cmp_gt_f32_e32 vcc, s82, v2
	s_nop 1
	v_cndmask_b32_e32 v2, v2, v14, vcc
	v_rsq_f32_e32 v2, v2
	v_lshl_add_u64 v[14:15], v[58:59], 0, s[8:9]
	global_store_short v[14:15], v1, off
	s_or_b64 s[8:9], s[36:37], s[12:13]
	v_mul_f32_e32 v1, 0x45800000, v2
	v_cndmask_b32_e32 v1, v2, v1, vcc
	v_add_f32_dpp v2, v92, v92 quad_perm:[1,0,3,2] row_mask:0xf bank_mask:0xf bound_ctrl:1
	v_mul_f32_e32 v1, v90, v1
	v_fma_f32 v1, v153, v1, v152
	v_add_f32_dpp v2, v2, v2 quad_perm:[2,3,0,1] row_mask:0xf bank_mask:0xf bound_ctrl:1
	v_fmac_f32_e32 v1, v3, v91
	s_lshl_b64 s[8:9], s[8:9], 10
	v_add_f32_dpp v2, v2, v2 row_half_mirror row_mask:0xf bank_mask:0xf bound_ctrl:1
	v_mul_f32_e32 v1, v5, v1
	v_cvt_pk_bf16_f32 v1, v1, v0
	s_nop 0
	v_add_f32_dpp v2, v2, v2 row_mirror row_mask:0xf bank_mask:0xf bound_ctrl:1
	s_nop 0
	s_nop 1
	v_add_f32_dpp v2, v2, v2 row_bcast:15 row_mask:0xa bank_mask:0xf
	s_nop 1
	v_add_f32_dpp v2, v2, v2 row_bcast:31 row_mask:0xc bank_mask:0xf
	s_nop 0
	v_readlane_b32 s2, v2, 63
	s_nop 1
	v_mov_b32_e32 v2, s2
	v_fmac_f32_e32 v92, 0xbc800000, v2
	v_mul_f32_e32 v2, v92, v92
	v_mov_b32_e32 v3, v0
	s_nop 1
	v_mov_b32_dpp v3, v2 quad_perm:[1,0,3,2] row_mask:0xf bank_mask:0xf
	v_fmac_f32_e32 v3, v92, v92
	s_nop 1
	v_add_f32_dpp v2, v3, v3 quad_perm:[2,3,0,1] row_mask:0xf bank_mask:0xf bound_ctrl:1
	s_nop 1
	v_add_f32_dpp v2, v2, v2 row_half_mirror row_mask:0xf bank_mask:0xf bound_ctrl:1
	s_nop 1
	v_add_f32_dpp v2, v2, v2 row_mirror row_mask:0xf bank_mask:0xf bound_ctrl:1
	s_nop 0
	s_nop 1
	v_add_f32_dpp v2, v2, v2 row_bcast:15 row_mask:0xa bank_mask:0xf
	s_nop 1
	v_add_f32_dpp v2, v2, v2 row_bcast:31 row_mask:0xc bank_mask:0xf
	s_nop 0
	v_readlane_b32 s2, v2, 63
	s_nop 1
	v_mov_b32_e32 v2, s2
	v_fmamk_f32 v2, v2, 0x3c800000, v233
	v_mul_f32_e32 v3, 0x4b800000, v2
	v_cmp_gt_f32_e32 vcc, s82, v2
	s_nop 1
	v_cndmask_b32_e32 v2, v2, v3, vcc
	v_rsq_f32_e32 v14, v2
	v_lshl_add_u64 v[2:3], v[58:59], 0, s[8:9]
	global_store_short v[2:3], v1, off
	s_or_b64 s[8:9], s[36:37], s[14:15]
	v_add_f32_dpp v2, v88, v88 quad_perm:[1,0,3,2] row_mask:0xf bank_mask:0xf bound_ctrl:1
	v_mul_f32_e32 v1, 0x45800000, v14
	v_cndmask_b32_e32 v1, v14, v1, vcc
	v_add_f32_dpp v2, v2, v2 quad_perm:[2,3,0,1] row_mask:0xf bank_mask:0xf bound_ctrl:1
	v_mul_f32_e32 v1, v92, v1
	v_fma_f32 v1, v153, v1, v152
	v_add_f32_dpp v2, v2, v2 row_half_mirror row_mask:0xf bank_mask:0xf bound_ctrl:1
	s_waitcnt lgkmcnt(0)
	v_fmac_f32_e32 v1, v12, v93
	v_mul_f32_e32 v1, v6, v1
	v_add_f32_dpp v2, v2, v2 row_mirror row_mask:0xf bank_mask:0xf bound_ctrl:1
	s_lshl_b64 s[8:9], s[8:9], 10
	v_cvt_pk_bf16_f32 v1, v1, v0
	s_nop 1
	v_add_f32_dpp v2, v2, v2 row_bcast:15 row_mask:0xa bank_mask:0xf
	s_nop 1
	v_add_f32_dpp v2, v2, v2 row_bcast:31 row_mask:0xc bank_mask:0xf
	s_nop 0
	v_readlane_b32 s2, v2, 63
	s_nop 1
	v_mov_b32_e32 v2, s2
	v_fmac_f32_e32 v88, 0xbc800000, v2
	v_mul_f32_e32 v2, v88, v88
	v_mov_b32_e32 v3, v0
	s_nop 1
	v_mov_b32_dpp v3, v2 quad_perm:[1,0,3,2] row_mask:0xf bank_mask:0xf
	v_fmac_f32_e32 v3, v88, v88
	s_nop 1
	v_add_f32_dpp v2, v3, v3 quad_perm:[2,3,0,1] row_mask:0xf bank_mask:0xf bound_ctrl:1
	s_nop 1
	v_add_f32_dpp v2, v2, v2 row_half_mirror row_mask:0xf bank_mask:0xf bound_ctrl:1
	s_nop 1
	v_add_f32_dpp v2, v2, v2 row_mirror row_mask:0xf bank_mask:0xf bound_ctrl:1
	s_nop 0
	s_nop 1
	v_add_f32_dpp v2, v2, v2 row_bcast:15 row_mask:0xa bank_mask:0xf
	s_nop 1
	v_add_f32_dpp v2, v2, v2 row_bcast:31 row_mask:0xc bank_mask:0xf
	s_nop 0
	v_readlane_b32 s2, v2, 63
	s_nop 1
	v_mov_b32_e32 v2, s2
	v_fmamk_f32 v2, v2, 0x3c800000, v233
	v_mul_f32_e32 v3, 0x4b800000, v2
	v_cmp_gt_f32_e32 vcc, s82, v2
	s_nop 1
	v_cndmask_b32_e32 v2, v2, v3, vcc
	v_rsq_f32_e32 v12, v2
	v_lshl_add_u64 v[2:3], v[58:59], 0, s[8:9]
	global_store_short v[2:3], v1, off
	s_or_b64 s[8:9], s[36:37], s[16:17]
	v_mul_f32_e32 v1, 0x45800000, v12
	v_cndmask_b32_e32 v1, v12, v1, vcc
	v_mul_f32_e32 v1, v88, v1
	v_fma_f32 v1, v153, v1, v152
	v_fmac_f32_e32 v1, v13, v94
	s_lshl_b64 s[8:9], s[8:9], 10
	v_mul_f32_e32 v1, v7, v1
	v_lshl_add_u64 v[2:3], v[58:59], 0, s[8:9]
	s_mov_b32 s8, s3
	v_cvt_pk_bf16_f32 v1, v1, v0
	global_store_short v[2:3], v1, off

.LBB0_508:
	v_ashrrev_i32_e32 v51, 31, v50
	v_lshlrev_b64 v[18:19], 12, v[50:51]
	v_lshl_add_u64 v[18:19], v[46:47], 0, v[18:19]
	global_load_dwordx4 v[74:77], v[18:19], off nt
	global_load_dwordx4 v[42:45], v[18:19], off offset:1024 nt
	global_load_dwordx4 v[38:41], v[18:19], off offset:2048 nt
	global_load_dwordx4 v[34:37], v[18:19], off offset:3072 nt
	v_ashrrev_i32_e32 v53, 10, v1
	v_add_u32_e32 v66, 1, v50
	v_mul_hi_i32_i24_e32 v61, 0x6000, v53
	v_mul_i32_i24_e32 v60, 0x6000, v53
	v_ashrrev_i32_e32 v67, 31, v66
	v_lshl_add_u64 v[60:61], s[6:7], 0, v[60:61]
	s_mov_b64 s[2:3], 0x1000
	v_lshlrev_b64 v[18:19], 12, v[66:67]
	v_lshl_add_u64 v[68:69], v[60:61], 0, s[2:3]
	v_mov_b32_e32 v53, v0
	v_lshl_add_u64 v[18:19], v[46:47], 0, v[18:19]
	v_lshl_add_u64 v[62:63], v[68:69], 0, v[52:53]
	global_load_dwordx4 v[30:33], v[18:19], off nt
	global_load_dwordx4 v[26:29], v[18:19], off offset:1024 nt
	global_load_dwordx4 v[22:25], v[18:19], off offset:2048 nt
	s_nop 0
	global_load_dwordx4 v[18:21], v[18:19], off offset:3072 nt
	v_lshl_add_u64 v[60:61], v[60:61], 0, v[52:53]
	v_add_u32_e32 v1, s33, v1
	global_load_dwordx4 v[82:85], v[60:61], off
	s_waitcnt vmcnt(8)
	v_pk_mul_f32 v[64:65], v[76:77], v[76:77]
	v_pk_mul_f32 v[70:71], v[74:75], v[74:75]
	s_waitcnt vmcnt(5)
	v_mul_f32_e32 v55, v34, v34
	v_pk_mov_b32 v[72:73], v[70:71], v[64:65] op_sel:[1,0]
	v_mov_b32_e32 v71, v65
	v_pk_add_f32 v[64:65], v[72:73], v[70:71]
	v_pk_mul_f32 v[70:71], v[44:45], v[44:45]
	v_pk_mul_f32 v[72:73], v[42:43], v[42:43]
	v_mul_f32_e32 v57, v35, v35
	v_pk_mov_b32 v[78:79], v[72:73], v[70:71] op_sel:[1,0]
	v_mov_b32_e32 v73, v71
	v_pk_add_f32 v[70:71], v[78:79], v[72:73]
	v_mul_f32_e32 v72, v41, v41
	v_mul_f32_e32 v78, v37, v37
	v_pk_fma_f32 v[72:73], v[40:41], v[40:41], v[72:73] op_sel_hi:[1,1,0]
	v_pk_add_f32 v[64:65], v[64:65], v[64:65] op_sel:[0,1] op_sel_hi:[1,0]
	v_mov_b32_e32 v73, v78
	global_load_dwordx4 v[78:81], v[62:63], off
	global_load_dwordx4 v[176:179], v[62:63], off
	global_load_dwordx4 v[180:183], v[62:63], off offset:1024
	global_load_dwordx4 v[184:187], v[62:63], off offset:2048
	global_load_dwordx4 v[188:191], v[62:63], off offset:3072
	global_load_dwordx4 v[192:195], v[60:61], off
	global_load_dwordx4 v[196:199], v[60:61], off offset:1024
	global_load_dwordx4 v[200:203], v[60:61], off offset:2048
	global_load_dwordx4 v[204:207], v[60:61], off offset:3072
	v_pk_add_f32 v[70:71], v[70:71], v[70:71] op_sel:[0,1] op_sel_hi:[1,0]
	v_mov_b32_e32 v65, v55
	v_mov_b32_e32 v71, v57
	v_pk_add_f32 v[64:65], v[64:65], v[70:71]
	v_mul_f32_e32 v70, v39, v39
	v_mul_f32_e32 v59, v36, v36
	v_pk_fma_f32 v[70:71], v[38:39], v[38:39], v[70:71] op_sel_hi:[1,1,0]
	s_waitcnt vmcnt(0)
	v_pk_add_f32 v[78:79], v[78:79], 1.0 op_sel_hi:[1,0]
	v_mov_b32_e32 v71, v59
	v_pk_add_f32 v[70:71], v[70:71], v[72:73]
	v_mov_b32_e32 v59, v0
	v_pk_add_f32 v[64:65], v[64:65], v[70:71]
	s_nop 0
	v_add_f32_e32 v55, v64, v65
	s_nop 1
	v_add_f32_dpp v55, v55, v55 quad_perm:[1,0,3,2] row_mask:0xf bank_mask:0xf bound_ctrl:1
	s_nop 1
	v_add_f32_dpp v55, v55, v55 quad_perm:[2,3,0,1] row_mask:0xf bank_mask:0xf bound_ctrl:1
	s_nop 1
	v_add_f32_dpp v55, v55, v55 row_half_mirror row_mask:0xf bank_mask:0xf bound_ctrl:1
	s_nop 1
	v_add_f32_dpp v55, v55, v55 row_mirror row_mask:0xf bank_mask:0xf bound_ctrl:1
	s_nop 0
	v_readlane_b32 s8, v55, 16
	v_readlane_b32 s9, v55, 48
	v_readlane_b32 s2, v55, 0
	v_readlane_b32 s3, v55, 32
	v_mov_b32_e32 v64, s8
	v_mov_b32_e32 v65, s9
	v_pk_add_f32 v[64:65], s[2:3], v[64:65]
	s_nop 0
	v_add_f32_e32 v55, v64, v65
	v_fmamk_f32 v55, v55, 0x3a800000, v162
	v_cmp_gt_f32_e32 vcc, s82, v55
	v_mul_f32_e32 v57, 0x4b800000, v55
	v_lshlrev_b64 v[64:65], 11, v[50:51]
	v_cndmask_b32_e32 v55, v55, v57, vcc
	v_rsq_f32_e32 v55, v55
	v_add_u32_e32 v50, s95, v50
	v_mul_f32_e32 v57, 0x45800000, v55
	v_cndmask_b32_e32 v72, v55, v57, vcc
	v_pk_mul_f32 v[70:71], v[76:77], v[72:73] op_sel_hi:[1,0]
	v_pk_mul_f32 v[74:75], v[74:75], v[72:73] op_sel_hi:[1,0]
	v_pk_mul_f32 v[70:71], v[4:5], v[70:71]
	v_pk_mul_f32 v[74:75], v[2:3], v[74:75]
	v_pk_add_f32 v[76:77], v[80:81], 1.0 op_sel_hi:[1,0]
	v_pk_fma_f32 v[74:75], v[78:79], v[74:75], v[82:83]
	v_pk_fma_f32 v[70:71], v[76:77], v[70:71], v[84:85]
	v_cvt_pk_bf16_f32 v74, v74, v75
	v_mov_b32_e32 v55, v0
	v_cvt_pk_bf16_f32 v75, v70, v71
	v_lshl_add_u64 v[70:71], v[48:49], 0, v[64:65]
	global_store_dwordx2 v[70:71], v[74:75], off
	v_lshl_add_u64 v[64:65], v[68:69], 0, v[54:55]
	v_mov_b64_e32 v[74:75], v[180:181]
	v_mov_b64_e32 v[76:77], v[182:183]
	v_mov_b64_e32 v[78:79], v[196:197]
	v_mov_b64_e32 v[80:81], v[198:199]
	v_pk_mul_f32 v[42:43], v[42:43], v[72:73] op_sel_hi:[1,0]
	v_pk_mul_f32 v[44:45], v[44:45], v[72:73] op_sel_hi:[1,0]
	v_pk_mul_f32 v[42:43], v[6:7], v[42:43]
	v_pk_mul_f32 v[44:45], v[8:9], v[44:45]
	v_mov_b32_e32 v57, v0
	v_pk_mul_f32 v[38:39], v[38:39], v[72:73] op_sel_hi:[1,0]
	v_pk_mul_f32 v[40:41], v[40:41], v[72:73] op_sel_hi:[1,0]
	v_pk_mul_f32 v[38:39], v[10:11], v[38:39]
	v_pk_mul_f32 v[40:41], v[12:13], v[40:41]
	v_pk_mul_f32 v[34:35], v[34:35], v[72:73] op_sel_hi:[1,0]
	v_pk_mul_f32 v[36:37], v[36:37], v[72:73] op_sel_hi:[1,0]
	v_pk_mul_f32 v[34:35], v[14:15], v[34:35]
	v_pk_mul_f32 v[36:37], v[16:17], v[36:37]
	v_pk_add_f32 v[74:75], v[74:75], 1.0 op_sel_hi:[1,0]
	v_pk_add_f32 v[76:77], v[76:77], 1.0 op_sel_hi:[1,0]
	v_pk_fma_f32 v[42:43], v[74:75], v[42:43], v[78:79]
	v_pk_fma_f32 v[44:45], v[76:77], v[44:45], v[80:81]
	v_cvt_pk_bf16_f32 v42, v42, v43
	s_nop 0
	v_cvt_pk_bf16_f32 v43, v44, v45
	global_store_dwordx2 v[70:71], v[42:43], off offset:512
	v_lshl_add_u64 v[42:43], v[68:69], 0, v[56:57]
	v_mov_b64_e32 v[74:75], v[184:185]
	v_mov_b64_e32 v[76:77], v[186:187]
	v_mov_b64_e32 v[78:79], v[200:201]
	v_mov_b64_e32 v[80:81], v[202:203]
	v_pk_add_f32 v[74:75], v[74:75], 1.0 op_sel_hi:[1,0]
	v_pk_add_f32 v[44:45], v[76:77], 1.0 op_sel_hi:[1,0]
	v_pk_fma_f32 v[38:39], v[74:75], v[38:39], v[78:79]
	v_pk_fma_f32 v[40:41], v[44:45], v[40:41], v[80:81]
	v_cvt_pk_bf16_f32 v38, v38, v39
	s_nop 0
	v_cvt_pk_bf16_f32 v39, v40, v41
	global_store_dwordx2 v[70:71], v[38:39], off offset:1024
	v_lshl_add_u64 v[38:39], v[68:69], 0, v[58:59]
	v_mov_b64_e32 v[74:75], v[188:189]
	v_mov_b64_e32 v[76:77], v[190:191]
	v_mov_b64_e32 v[78:79], v[204:205]
	v_mov_b64_e32 v[80:81], v[206:207]
	v_pk_add_f32 v[44:45], v[74:75], 1.0 op_sel_hi:[1,0]
	v_pk_add_f32 v[40:41], v[76:77], 1.0 op_sel_hi:[1,0]
	v_pk_fma_f32 v[34:35], v[34:35], v[44:45], v[78:79]
	v_pk_fma_f32 v[36:37], v[36:37], v[40:41], v[80:81]
	v_cvt_pk_bf16_f32 v34, v34, v35
	s_nop 0
	v_cvt_pk_bf16_f32 v35, v36, v37
	global_store_dwordx2 v[70:71], v[34:35], off offset:1536
	v_pk_mul_f32 v[34:35], v[32:33], v[32:33]
	v_pk_mul_f32 v[36:37], v[30:31], v[30:31]
	s_nop 0
	v_pk_mov_b32 v[40:41], v[36:37], v[34:35] op_sel:[1,0]
	v_mov_b32_e32 v37, v35
	v_pk_add_f32 v[34:35], v[40:41], v[36:37]
	v_pk_mul_f32 v[36:37], v[28:29], v[28:29]
	v_pk_mul_f32 v[40:41], v[26:27], v[26:27]
	v_pk_add_f32 v[34:35], v[34:35], v[34:35] op_sel:[0,1] op_sel_hi:[1,0]
	v_pk_mov_b32 v[44:45], v[40:41], v[36:37] op_sel:[1,0]
	v_mov_b32_e32 v41, v37
	v_pk_add_f32 v[36:37], v[44:45], v[40:41]
	v_mul_f32_e32 v40, v18, v18
	v_mul_f32_e32 v41, v19, v19
	v_pk_add_f32 v[36:37], v[36:37], v[36:37] op_sel:[0,1] op_sel_hi:[1,0]
	v_mov_b32_e32 v35, v40
	v_mov_b32_e32 v37, v41
	v_pk_add_f32 v[34:35], v[34:35], v[36:37]
	v_mul_f32_e32 v36, v23, v23
	v_mul_f32_e32 v40, v25, v25
	v_mul_f32_e32 v44, v20, v20
	v_mul_f32_e32 v45, v21, v21
	v_pk_fma_f32 v[36:37], v[22:23], v[22:23], v[36:37] op_sel_hi:[1,1,0]
	v_pk_fma_f32 v[40:41], v[24:25], v[24:25], v[40:41] op_sel_hi:[1,1,0]
	v_mov_b32_e32 v37, v44
	v_mov_b32_e32 v41, v45
	v_pk_add_f32 v[36:37], v[36:37], v[40:41]
	s_nop 0
	v_pk_add_f32 v[34:35], v[34:35], v[36:37]
	v_lshlrev_b64 v[36:37], 11, v[66:67]
	v_mov_b64_e32 v[66:67], v[176:177]
	v_mov_b64_e32 v[68:69], v[178:179]
	v_mov_b64_e32 v[70:71], v[192:193]
	v_mov_b64_e32 v[72:73], v[194:195]
	v_add_f32_e32 v34, v34, v35
	v_pk_add_f32 v[44:45], v[66:67], 1.0 op_sel_hi:[1,0]
	s_nop 0
	v_add_f32_dpp v34, v34, v34 quad_perm:[1,0,3,2] row_mask:0xf bank_mask:0xf bound_ctrl:1
	v_pk_add_f32 v[40:41], v[68:69], 1.0 op_sel_hi:[1,0]
	s_nop 0
	v_add_f32_dpp v34, v34, v34 quad_perm:[2,3,0,1] row_mask:0xf bank_mask:0xf bound_ctrl:1
	s_nop 1
	v_add_f32_dpp v34, v34, v34 row_half_mirror row_mask:0xf bank_mask:0xf bound_ctrl:1
	s_nop 1
	v_add_f32_dpp v34, v34, v34 row_mirror row_mask:0xf bank_mask:0xf bound_ctrl:1
	s_nop 0
	v_readlane_b32 s8, v34, 16
	v_readlane_b32 s9, v34, 48
	v_readlane_b32 s2, v34, 0
	v_readlane_b32 s3, v34, 32
	v_mov_b32_e32 v34, s8
	v_mov_b32_e32 v35, s9
	v_pk_add_f32 v[34:35], s[2:3], v[34:35]
	s_nop 0
	v_add_f32_e32 v34, v34, v35
	v_fmamk_f32 v34, v34, 0x3a800000, v162
	v_cmp_gt_f32_e32 vcc, s82, v34
	v_mul_f32_e32 v35, 0x4b800000, v34
	s_nop 0
	v_cndmask_b32_e32 v34, v34, v35, vcc
	v_rsq_f32_e32 v34, v34
	s_nop 0
	v_mul_f32_e32 v35, 0x45800000, v34
	v_cndmask_b32_e32 v34, v34, v35, vcc
	v_pk_mul_f32 v[30:31], v[30:31], v[34:35] op_sel_hi:[1,0]
	v_pk_mul_f32 v[32:33], v[32:33], v[34:35] op_sel_hi:[1,0]
	v_pk_mul_f32 v[30:31], v[2:3], v[30:31]
	v_pk_mul_f32 v[32:33], v[4:5], v[32:33]
	v_pk_fma_f32 v[30:31], v[44:45], v[30:31], v[70:71]
	v_pk_fma_f32 v[40:41], v[40:41], v[32:33], v[72:73]
	v_cvt_pk_bf16_f32 v32, v30, v31
	v_lshl_add_u64 v[30:31], v[48:49], 0, v[36:37]
	v_cvt_pk_bf16_f32 v33, v40, v41
	global_store_dwordx2 v[30:31], v[32:33], off
	v_mov_b64_e32 v[62:63], v[180:181]
	v_mov_b64_e32 v[64:65], v[182:183]
	s_nop 0
	v_mov_b64_e32 v[66:67], v[196:197]
	v_mov_b64_e32 v[68:69], v[198:199]
	v_pk_mul_f32 v[26:27], v[26:27], v[34:35] op_sel_hi:[1,0]
	v_pk_mul_f32 v[28:29], v[28:29], v[34:35] op_sel_hi:[1,0]
	v_pk_mul_f32 v[26:27], v[6:7], v[26:27]
	v_pk_mul_f32 v[28:29], v[8:9], v[28:29]
	v_pk_mul_f32 v[22:23], v[22:23], v[34:35] op_sel_hi:[1,0]
	v_pk_mul_f32 v[24:25], v[24:25], v[34:35] op_sel_hi:[1,0]
	v_pk_mul_f32 v[22:23], v[10:11], v[22:23]
	v_pk_mul_f32 v[24:25], v[12:13], v[24:25]
	v_pk_mul_f32 v[18:19], v[18:19], v[34:35] op_sel_hi:[1,0]
	v_pk_mul_f32 v[20:21], v[20:21], v[34:35] op_sel_hi:[1,0]
	v_pk_mul_f32 v[18:19], v[14:15], v[18:19]
	v_cmp_lt_i32_e32 vcc, s34, v1
	v_pk_mul_f32 v[20:21], v[16:17], v[20:21]
	s_or_b64 s[0:1], vcc, s[0:1]
	v_pk_add_f32 v[36:37], v[62:63], 1.0 op_sel_hi:[1,0]
	v_pk_add_f32 v[32:33], v[64:65], 1.0 op_sel_hi:[1,0]
	v_pk_fma_f32 v[26:27], v[36:37], v[26:27], v[66:67]
	v_pk_fma_f32 v[28:29], v[32:33], v[28:29], v[68:69]
	v_cvt_pk_bf16_f32 v26, v26, v27
	s_nop 0
	v_cvt_pk_bf16_f32 v27, v28, v29
	global_store_dwordx2 v[30:31], v[26:27], off offset:512
	v_mov_b64_e32 v[26:27], v[184:185]
	v_mov_b64_e32 v[28:29], v[186:187]
	s_nop 0
	v_mov_b64_e32 v[40:41], v[200:201]
	v_mov_b64_e32 v[42:43], v[202:203]
	v_pk_add_f32 v[26:27], v[26:27], 1.0 op_sel_hi:[1,0]
	v_pk_add_f32 v[28:29], v[28:29], 1.0 op_sel_hi:[1,0]
	v_pk_fma_f32 v[22:23], v[26:27], v[22:23], v[40:41]
	v_pk_fma_f32 v[24:25], v[28:29], v[24:25], v[42:43]
	v_cvt_pk_bf16_f32 v22, v22, v23
	s_nop 0
	v_cvt_pk_bf16_f32 v23, v24, v25
	global_store_dwordx2 v[30:31], v[22:23], off offset:1024
	v_mov_b64_e32 v[22:23], v[188:189]
	v_mov_b64_e32 v[24:25], v[190:191]
	s_nop 0
	v_mov_b64_e32 v[26:27], v[204:205]
	v_mov_b64_e32 v[28:29], v[206:207]
	v_pk_add_f32 v[22:23], v[22:23], 1.0 op_sel_hi:[1,0]
	v_pk_add_f32 v[24:25], v[24:25], 1.0 op_sel_hi:[1,0]
	v_pk_fma_f32 v[18:19], v[18:19], v[22:23], v[26:27]
	v_pk_fma_f32 v[20:21], v[20:21], v[24:25], v[28:29]
	v_cvt_pk_bf16_f32 v18, v18, v19
	s_nop 0
	v_cvt_pk_bf16_f32 v19, v20, v21
	global_store_dwordx2 v[30:31], v[18:19], off offset:1536
	s_andn2_b64 exec, exec, s[0:1]
	s_cbranch_execnz .LBB0_508
	s_branch .LBB0_7
